# fox attention queue: one static s_setprio 1 for the younger wave half (waves 4-7), reset at the end of the phase
# baseline (speedup 1.0000x reference)
.Lfox_pf_skip:
	s_or_b64 exec, exec, s[2:3]
	s_mov_b32 s100, 1
	v_readfirstlane_b32 s2, v0
	s_cmpk_lt_u32 s2, 0x100
	s_cbranch_scc1 .Lfox_prio_skip
	s_setprio 1
.Lfox_prio_skip:
	s_waitcnt lgkmcnt(0)
	s_waitcnt lgkmcnt(0)
	ds_read_b128 v[34:37], v226
	ds_read_b128 v[52:55], v226 offset:32
	v_readlane_b32 s36, v253, 20
	v_readlane_b32 s44, v253, 28
	v_readlane_b32 s45, v253, 29
	s_waitcnt lgkmcnt(1)
	v_rcp_f32_e32 v34, v34
	v_readlane_b32 s37, v253, 21
	v_readlane_b32 s38, v253, 22
	v_readlane_b32 s39, v253, 23
	v_mul_f32_e32 v47, v2, v34
	v_rcp_f32_e32 v2, v35
	v_mul_f32_e32 v46, v18, v34
	v_mul_f32_e32 v49, v46, v46
	v_fmac_f32_e32 v49, v47, v47
	v_mul_f32_e32 v45, v3, v2
	v_mul_f32_e32 v44, v19, v2
	v_rcp_f32_e32 v2, v36
	v_mul_f32_e32 v50, v44, v44
	v_fmac_f32_e32 v50, v45, v45
	v_readlane_b32 s40, v253, 24
	v_mul_f32_e32 v43, v4, v2
	v_mul_f32_e32 v42, v20, v2
	v_rcp_f32_e32 v2, v37
	v_mul_f32_e32 v51, v42, v42
	v_fmac_f32_e32 v51, v43, v43
	v_readlane_b32 s41, v253, 25
	v_mul_f32_e32 v41, v5, v2
	v_mul_f32_e32 v40, v21, v2
	s_waitcnt lgkmcnt(0)
	v_rcp_f32_e32 v2, v52
	v_mul_f32_e32 v56, v40, v40
	v_fmac_f32_e32 v56, v41, v41
	v_readlane_b32 s42, v253, 26
	v_mul_f32_e32 v39, v6, v2
	v_mul_f32_e32 v38, v22, v2
	v_rcp_f32_e32 v2, v53
	v_mul_f32_e32 v52, v38, v38
	v_fmac_f32_e32 v52, v39, v39
	v_readlane_b32 s43, v253, 27
	v_mul_f32_e32 v37, v7, v2
	v_mul_f32_e32 v36, v23, v2
	v_rcp_f32_e32 v2, v54
	v_mul_f32_e32 v53, v36, v36
	v_fmac_f32_e32 v53, v37, v37
	v_readlane_b32 s46, v253, 30
	v_mul_f32_e32 v35, v8, v2
	v_mul_f32_e32 v34, v24, v2
	v_rcp_f32_e32 v2, v55
	v_mul_f32_e32 v54, v34, v34
	v_fmac_f32_e32 v54, v35, v35
	v_readlane_b32 s47, v253, 31
	v_mul_f32_e32 v24, v9, v2
	v_mul_f32_e32 v23, v25, v2
	ds_read_b128 v[2:5], v226 offset:64
	v_mul_f32_e32 v25, v23, v23
	v_fmac_f32_e32 v25, v24, v24
	v_readlane_b32 s48, v253, 32
	v_readlane_b32 s49, v253, 33
	s_waitcnt lgkmcnt(0)
	v_rcp_f32_e32 v2, v2
	v_readlane_b32 s50, v253, 34
	v_readlane_b32 s51, v253, 35
	v_mul_f32_e32 v22, v10, v2
	v_mul_f32_e32 v21, v26, v2
	v_rcp_f32_e32 v2, v3
	v_mul_f32_e32 v55, v21, v21
	v_fmac_f32_e32 v55, v22, v22
	v_mul_f32_e32 v20, v11, v2
	v_mul_f32_e32 v19, v27, v2
	v_rcp_f32_e32 v2, v4
	v_mul_f32_e32 v57, v19, v19
	v_fmac_f32_e32 v57, v20, v20
	v_mul_f32_e32 v18, v12, v2
	v_mul_f32_e32 v11, v28, v2
	v_rcp_f32_e32 v2, v5
	v_mul_f32_e32 v58, v11, v11
	v_fmac_f32_e32 v58, v18, v18
	v_mul_f32_e32 v6, v29, v2
	ds_read_b128 v[26:29], v226 offset:96
	v_mul_f32_e32 v7, v13, v2
	v_mul_f32_e32 v13, v6, v6
	v_fmac_f32_e32 v13, v7, v7
	s_waitcnt lgkmcnt(0)
	v_rcp_f32_e32 v2, v26
	v_xor_b32_e32 v26, 1, v240
	v_cmp_lt_i32_e32 vcc, v26, v48
	v_mul_f32_e32 v12, v14, v2
	v_mul_f32_e32 v10, v30, v2
	v_rcp_f32_e32 v2, v27
	v_cndmask_b32_e32 v26, v240, v26, vcc
	v_lshlrev_b32_e32 v26, 2, v26
	v_mul_f32_e32 v14, v10, v10
	v_mul_f32_e32 v8, v31, v2
	ds_bpermute_b32 v31, v26, v52
	v_fmac_f32_e32 v14, v12, v12
	v_mul_f32_e32 v9, v15, v2
	v_rcp_f32_e32 v2, v28
	ds_bpermute_b32 v27, v26, v49
	s_waitcnt lgkmcnt(1)
	v_add_f32_e32 v31, v52, v31
	ds_bpermute_b32 v52, v26, v13
	v_mul_f32_e32 v15, v8, v8
	v_mul_f32_e32 v5, v16, v2
	v_mul_f32_e32 v4, v32, v2
	v_rcp_f32_e32 v2, v29
	s_waitcnt lgkmcnt(0)
	v_add_f32_e32 v13, v13, v52
	ds_bpermute_b32 v52, v26, v14
	v_fmac_f32_e32 v15, v9, v9
	v_add_f32_e32 v27, v49, v27
	ds_bpermute_b32 v28, v26, v50
	ds_bpermute_b32 v29, v26, v51
	ds_bpermute_b32 v49, v26, v25
	s_waitcnt lgkmcnt(3)
	v_add_f32_e32 v14, v14, v52
	ds_bpermute_b32 v52, v26, v15
	v_mul_f32_e32 v3, v17, v2
	v_mul_f32_e32 v2, v33, v2
	v_mul_f32_e32 v16, v4, v4
	v_mul_f32_e32 v17, v2, v2
	v_fmac_f32_e32 v16, v5, v5
	v_fmac_f32_e32 v17, v3, v3
	s_waitcnt lgkmcnt(3)
	v_add_f32_e32 v28, v50, v28
	s_waitcnt lgkmcnt(2)
	v_add_f32_e32 v29, v51, v29
	ds_bpermute_b32 v30, v26, v56
	ds_bpermute_b32 v32, v26, v53
	ds_bpermute_b32 v33, v26, v54
	s_waitcnt lgkmcnt(4)
	v_add_f32_e32 v25, v25, v49
	ds_bpermute_b32 v49, v26, v55
	ds_bpermute_b32 v50, v26, v57
	ds_bpermute_b32 v51, v26, v58
	s_waitcnt lgkmcnt(6)
	v_add_f32_e32 v15, v15, v52
	ds_bpermute_b32 v52, v26, v16
	ds_bpermute_b32 v26, v26, v17
	s_waitcnt lgkmcnt(7)
	v_add_f32_e32 v30, v56, v30
	s_waitcnt lgkmcnt(6)
	v_add_f32_e32 v32, v53, v32
	s_waitcnt lgkmcnt(5)
	v_add_f32_e32 v33, v54, v33
	s_waitcnt lgkmcnt(1)
	v_add_f32_e32 v16, v16, v52
	s_waitcnt lgkmcnt(0)
	v_add_f32_e32 v17, v17, v26
	v_xor_b32_e32 v26, 2, v240
	v_cmp_lt_i32_e32 vcc, v26, v48
	v_add_f32_e32 v49, v55, v49
	v_add_f32_e32 v50, v57, v50
	v_cndmask_b32_e32 v26, v240, v26, vcc
	v_lshlrev_b32_e32 v26, 2, v26
	ds_bpermute_b32 v52, v26, v27
	v_add_f32_e32 v51, v58, v51
	s_waitcnt lgkmcnt(0)
	v_add_f32_e32 v27, v27, v52
	ds_bpermute_b32 v52, v26, v28
	s_waitcnt lgkmcnt(0)
	v_add_f32_e32 v28, v28, v52
	ds_bpermute_b32 v52, v26, v29
	s_waitcnt lgkmcnt(0)
	v_add_f32_e32 v29, v29, v52
	ds_bpermute_b32 v52, v26, v30
	s_waitcnt lgkmcnt(0)
	v_add_f32_e32 v30, v30, v52
	ds_bpermute_b32 v52, v26, v31
	s_waitcnt lgkmcnt(0)
	v_add_f32_e32 v31, v31, v52
	ds_bpermute_b32 v52, v26, v32
	s_waitcnt lgkmcnt(0)
	v_add_f32_e32 v32, v32, v52
	ds_bpermute_b32 v52, v26, v33
	s_waitcnt lgkmcnt(0)
	v_add_f32_e32 v33, v33, v52
	ds_bpermute_b32 v52, v26, v25
	s_waitcnt lgkmcnt(0)
	v_add_f32_e32 v25, v25, v52
	ds_bpermute_b32 v52, v26, v49
	s_waitcnt lgkmcnt(0)
	v_add_f32_e32 v49, v49, v52
	ds_bpermute_b32 v52, v26, v50
	s_waitcnt lgkmcnt(0)
	v_add_f32_e32 v50, v50, v52
	ds_bpermute_b32 v52, v26, v51
	s_waitcnt lgkmcnt(0)
	v_add_f32_e32 v51, v51, v52
	ds_bpermute_b32 v52, v26, v13
	s_waitcnt lgkmcnt(0)
	v_add_f32_e32 v13, v13, v52
	ds_bpermute_b32 v52, v26, v14
	s_waitcnt lgkmcnt(0)
	v_add_f32_e32 v14, v14, v52
	ds_bpermute_b32 v52, v26, v15
	s_waitcnt lgkmcnt(0)
	v_add_f32_e32 v15, v15, v52
	ds_bpermute_b32 v52, v26, v16
	ds_bpermute_b32 v26, v26, v17
	s_waitcnt lgkmcnt(1)
	v_add_f32_e32 v16, v16, v52
	s_waitcnt lgkmcnt(0)
	v_add_f32_e32 v17, v17, v26
	v_xor_b32_e32 v26, 4, v240
	v_cmp_lt_i32_e32 vcc, v26, v48
	s_nop 1
	v_cndmask_b32_e32 v26, v240, v26, vcc
	v_lshlrev_b32_e32 v26, 2, v26
	ds_bpermute_b32 v52, v26, v27
	s_waitcnt lgkmcnt(0)
	v_add_f32_e32 v27, v27, v52
	ds_bpermute_b32 v52, v26, v28
	s_waitcnt lgkmcnt(0)
	v_add_f32_e32 v28, v28, v52
	ds_bpermute_b32 v52, v26, v29
	s_waitcnt lgkmcnt(0)
	v_add_f32_e32 v29, v29, v52
	ds_bpermute_b32 v52, v26, v30
	s_waitcnt lgkmcnt(0)
	v_add_f32_e32 v30, v30, v52
	ds_bpermute_b32 v52, v26, v31
	s_waitcnt lgkmcnt(0)
	v_add_f32_e32 v31, v31, v52
	ds_bpermute_b32 v52, v26, v32
	s_waitcnt lgkmcnt(0)
	v_add_f32_e32 v32, v32, v52
	ds_bpermute_b32 v52, v26, v33
	s_waitcnt lgkmcnt(0)
	v_add_f32_e32 v33, v33, v52
	ds_bpermute_b32 v52, v26, v25
	s_waitcnt lgkmcnt(0)
	v_add_f32_e32 v25, v25, v52
	ds_bpermute_b32 v52, v26, v49
	s_waitcnt lgkmcnt(0)
	v_add_f32_e32 v49, v49, v52
	ds_bpermute_b32 v52, v26, v50
	s_waitcnt lgkmcnt(0)
	v_add_f32_e32 v50, v50, v52
	ds_bpermute_b32 v52, v26, v51
	s_waitcnt lgkmcnt(0)
	v_add_f32_e32 v51, v51, v52
	ds_bpermute_b32 v52, v26, v13
	s_waitcnt lgkmcnt(0)
	v_add_f32_e32 v13, v13, v52
	ds_bpermute_b32 v52, v26, v14
	s_waitcnt lgkmcnt(0)
	v_add_f32_e32 v14, v14, v52
	ds_bpermute_b32 v52, v26, v15
	s_waitcnt lgkmcnt(0)
	v_add_f32_e32 v15, v15, v52
	ds_bpermute_b32 v52, v26, v16
	ds_bpermute_b32 v26, v26, v17
	s_waitcnt lgkmcnt(1)
	v_add_f32_e32 v16, v16, v52
	s_waitcnt lgkmcnt(0)
	v_add_f32_e32 v17, v17, v26
	v_xor_b32_e32 v26, 8, v240
	v_cmp_lt_i32_e32 vcc, v26, v48
	s_nop 1
	v_cndmask_b32_e32 v26, v240, v26, vcc
	v_lshlrev_b32_e32 v26, 2, v26
	ds_bpermute_b32 v52, v26, v27
	s_waitcnt lgkmcnt(0)
	v_add_f32_e32 v27, v27, v52
	ds_bpermute_b32 v52, v26, v28
	s_waitcnt lgkmcnt(0)
	v_add_f32_e32 v28, v28, v52
	ds_bpermute_b32 v52, v26, v29
	s_waitcnt lgkmcnt(0)
	v_add_f32_e32 v29, v29, v52
	ds_bpermute_b32 v52, v26, v30
	s_waitcnt lgkmcnt(0)
	v_add_f32_e32 v30, v30, v52
	ds_bpermute_b32 v52, v26, v31
	s_waitcnt lgkmcnt(0)
	v_add_f32_e32 v31, v31, v52
	ds_bpermute_b32 v52, v26, v32
	s_waitcnt lgkmcnt(0)
	v_add_f32_e32 v32, v32, v52
	ds_bpermute_b32 v52, v26, v33
	s_waitcnt lgkmcnt(0)
	v_add_f32_e32 v52, v33, v52
	ds_bpermute_b32 v33, v26, v25
	s_waitcnt lgkmcnt(0)
	v_add_f32_e32 v25, v25, v33
	ds_bpermute_b32 v33, v26, v49
	s_waitcnt lgkmcnt(0)
	v_add_f32_e32 v53, v49, v33
	ds_bpermute_b32 v33, v26, v50
	s_waitcnt lgkmcnt(0)
	v_add_f32_e32 v50, v50, v33
	ds_bpermute_b32 v33, v26, v51
	s_waitcnt lgkmcnt(0)
	v_add_f32_e32 v51, v51, v33
	ds_bpermute_b32 v33, v26, v13
	s_waitcnt lgkmcnt(0)
	v_add_f32_e32 v13, v13, v33
	ds_bpermute_b32 v33, v26, v14
	s_waitcnt lgkmcnt(0)
	v_add_f32_e32 v14, v14, v33
	ds_bpermute_b32 v33, v26, v15
	s_waitcnt lgkmcnt(0)
	v_add_f32_e32 v15, v15, v33
	ds_bpermute_b32 v33, v26, v16
	ds_bpermute_b32 v26, v26, v17
	s_waitcnt lgkmcnt(1)
	v_add_f32_e32 v16, v16, v33
	s_waitcnt lgkmcnt(0)
	v_add_f32_e32 v54, v17, v26
	v_xor_b32_e32 v17, 16, v240
	v_cmp_lt_i32_e32 vcc, v17, v48
	s_nop 1
	v_cndmask_b32_e32 v17, v240, v17, vcc
	v_lshlrev_b32_e32 v55, 2, v17
	ds_bpermute_b32 v17, v55, v27
	s_waitcnt lgkmcnt(0)
	v_add_f32_e32 v56, v27, v17
	ds_bpermute_b32 v17, v55, v28
	s_waitcnt lgkmcnt(0)
	v_add_f32_e32 v57, v28, v17
	ds_bpermute_b32 v17, v55, v29
	s_waitcnt lgkmcnt(0)
	v_add_f32_e32 v49, v29, v17
	ds_bpermute_b32 v17, v55, v30
	s_waitcnt lgkmcnt(0)
	v_add_f32_e32 v48, v30, v17
	ds_bpermute_b32 v17, v55, v31
	s_waitcnt lgkmcnt(0)
	v_add_f32_e32 v33, v31, v17
	ds_bpermute_b32 v17, v55, v32
	v_fmamk_f32 v33, v33, 0x3c800000, v233
	s_waitcnt lgkmcnt(0)
	v_add_f32_e32 v32, v32, v17
	ds_bpermute_b32 v17, v55, v52
	v_fmamk_f32 v32, v32, 0x3c800000, v233
	s_waitcnt lgkmcnt(0)
	v_add_f32_e32 v31, v52, v17
	ds_bpermute_b32 v17, v55, v25
	v_fmamk_f32 v31, v31, 0x3c800000, v233
	s_waitcnt lgkmcnt(0)
	v_add_f32_e32 v30, v25, v17
	ds_bpermute_b32 v17, v55, v53
	v_fmamk_f32 v30, v30, 0x3c800000, v233
	s_waitcnt lgkmcnt(0)
	v_add_f32_e32 v29, v53, v17
	ds_bpermute_b32 v17, v55, v50
	s_waitcnt lgkmcnt(0)
	v_add_f32_e32 v28, v50, v17
	ds_bpermute_b32 v17, v55, v51
	v_fmamk_f32 v50, v56, 0x3c800000, v233
	v_cmp_gt_f32_e32 vcc, s19, v50
	s_waitcnt lgkmcnt(0)
	v_add_f32_e32 v27, v51, v17
	ds_bpermute_b32 v17, v55, v13
	v_mul_f32_e32 v51, 0x4f800000, v50
	v_cndmask_b32_e32 v50, v50, v51, vcc
	v_sqrt_f32_e32 v51, v50
	s_waitcnt lgkmcnt(0)
	v_add_f32_e32 v26, v13, v17
	ds_bpermute_b32 v13, v55, v14
	v_add_u32_e32 v52, -1, v51
	v_fma_f32 v53, -v52, v51, v50
	v_cmp_ge_f32_e64 s[82:83], 0, v53
	v_add_u32_e32 v53, 1, v51
	s_waitcnt lgkmcnt(0)
	v_add_f32_e32 v25, v14, v13
	ds_bpermute_b32 v13, v55, v15
	v_cndmask_b32_e64 v52, v51, v52, s[82:83]
	v_fma_f32 v51, -v53, v51, v50
	v_cmp_lt_f32_e64 s[82:83], 0, v51
	s_waitcnt lgkmcnt(0)
	v_add_f32_e32 v17, v15, v13
	ds_bpermute_b32 v13, v55, v16
	v_or_b32_e32 v15, s24, v181
	v_cndmask_b32_e64 v51, v52, v53, s[82:83]
	v_mul_f32_e32 v52, 0x37800000, v51
	v_cndmask_b32_e32 v51, v51, v52, vcc
	s_waitcnt lgkmcnt(0)
	v_add_f32_e32 v14, v16, v13
	v_lshlrev_b32_e32 v16, 2, v15
	global_load_dword v15, v16, s[44:45]
	s_nop 0
	global_load_dword v16, v16, s[44:45] offset:128
	v_cmp_class_f32_e32 vcc, v50, v234
	ds_bpermute_b32 v13, v55, v54
	s_waitcnt lgkmcnt(0)
	v_add_f32_e32 v13, v54, v13
	v_cndmask_b32_e32 v50, v51, v50, vcc
	v_div_scale_f32 v51, s[2:3], v50, v50, 1.0
	v_rcp_f32_e32 v52, v51
	s_nop 0
	v_fma_f32 v53, -v51, v52, 1.0
	v_fmac_f32_e32 v52, v53, v52
	v_div_scale_f32 v53, vcc, 1.0, v50, 1.0
	v_mul_f32_e32 v54, v53, v52
	v_fma_f32 v55, -v51, v54, v53
	v_fmac_f32_e32 v54, v55, v52
	v_fma_f32 v51, -v51, v54, v53
	v_div_fmas_f32 v51, v51, v52, v54
	v_div_fixup_f32 v50, v51, v50, 1.0
	v_mul_f32_e32 v47, v47, v50
	v_mul_f32_e32 v46, v46, v50
	s_waitcnt vmcnt(1)
	v_mul_f32_e32 v47, v47, v15
	v_bfe_u32 v51, v47, 16, 1
	v_add3_u32 v47, v47, v51, s22
	s_waitcnt vmcnt(0)
	v_mul_f32_e32 v46, v46, v16
	ds_write_b16_d16_hi v235, v47
	v_bfe_u32 v47, v46, 16, 1
	v_add3_u32 v46, v46, v47, s22
	ds_write_b16_d16_hi v235, v46 offset:64
	v_fmamk_f32 v46, v57, 0x3c800000, v233
	v_cmp_gt_f32_e32 vcc, s19, v46
	v_mul_f32_e32 v47, 0x4f800000, v46
	s_nop 0
	v_cndmask_b32_e32 v46, v46, v47, vcc
	v_sqrt_f32_e32 v47, v46
	s_nop 0
	v_add_u32_e32 v50, -1, v47
	v_fma_f32 v51, -v50, v47, v46
	v_cmp_ge_f32_e64 s[82:83], 0, v51
	v_add_u32_e32 v51, 1, v47
	s_nop 0
	v_cndmask_b32_e64 v50, v47, v50, s[82:83]
	v_fma_f32 v47, -v51, v47, v46
	v_cmp_lt_f32_e64 s[82:83], 0, v47
	s_nop 1
	v_cndmask_b32_e64 v47, v50, v51, s[82:83]
	v_mul_f32_e32 v50, 0x37800000, v47
	v_cndmask_b32_e32 v47, v47, v50, vcc
	v_cmp_class_f32_e32 vcc, v46, v234
	s_nop 1
	v_cndmask_b32_e32 v46, v47, v46, vcc
	v_div_scale_f32 v47, s[2:3], v46, v46, 1.0
	v_rcp_f32_e32 v50, v47
	s_nop 0
	v_fma_f32 v51, -v47, v50, 1.0
	v_fmac_f32_e32 v50, v51, v50
	v_div_scale_f32 v51, vcc, 1.0, v46, 1.0
	v_mul_f32_e32 v52, v51, v50
	v_fma_f32 v53, -v47, v52, v51
	v_fmac_f32_e32 v52, v53, v50
	v_fma_f32 v47, -v47, v52, v51
	v_div_fmas_f32 v47, v47, v50, v52
	v_div_fixup_f32 v46, v47, v46, 1.0
	v_mul_f32_e32 v45, v45, v46
	v_mul_f32_e32 v45, v45, v15
	v_bfe_u32 v47, v45, 16, 1
	v_mul_f32_e32 v44, v44, v46
	v_add3_u32 v45, v45, v47, s22
	v_mul_f32_e32 v44, v44, v16
	ds_write_b16_d16_hi v235, v45 offset:128
	v_bfe_u32 v45, v44, 16, 1
	v_add3_u32 v44, v44, v45, s22
	ds_write_b16_d16_hi v235, v44 offset:192
	v_fmamk_f32 v44, v49, 0x3c800000, v233
	v_cmp_gt_f32_e32 vcc, s19, v44
	v_mul_f32_e32 v45, 0x4f800000, v44
	s_nop 0
	v_cndmask_b32_e32 v44, v44, v45, vcc
	v_sqrt_f32_e32 v45, v44
	s_nop 0
	v_add_u32_e32 v46, -1, v45
	v_fma_f32 v47, -v46, v45, v44
	v_cmp_ge_f32_e64 s[82:83], 0, v47
	v_add_u32_e32 v47, 1, v45
	s_nop 0
	v_cndmask_b32_e64 v46, v45, v46, s[82:83]
	v_fma_f32 v45, -v47, v45, v44
	v_cmp_lt_f32_e64 s[82:83], 0, v45
	s_nop 1
	v_cndmask_b32_e64 v45, v46, v47, s[82:83]
	v_mul_f32_e32 v46, 0x37800000, v45
	v_cndmask_b32_e32 v45, v45, v46, vcc
	v_cmp_class_f32_e32 vcc, v44, v234
	s_nop 1
	v_cndmask_b32_e32 v44, v45, v44, vcc
	v_div_scale_f32 v45, s[2:3], v44, v44, 1.0
	v_rcp_f32_e32 v46, v45
	s_nop 0
	v_fma_f32 v47, -v45, v46, 1.0
	v_fmac_f32_e32 v46, v47, v46
	v_div_scale_f32 v47, vcc, 1.0, v44, 1.0
	v_mul_f32_e32 v49, v47, v46
	v_fma_f32 v50, -v45, v49, v47
	v_fmac_f32_e32 v49, v50, v46
	v_fma_f32 v45, -v45, v49, v47
	v_div_fmas_f32 v45, v45, v46, v49
	v_div_fixup_f32 v44, v45, v44, 1.0
	v_mul_f32_e32 v43, v43, v44
	v_mul_f32_e32 v43, v43, v15
	v_bfe_u32 v45, v43, 16, 1
	v_mul_f32_e32 v42, v42, v44
	v_add3_u32 v43, v43, v45, s22
	v_mul_f32_e32 v42, v42, v16
	ds_write_b16_d16_hi v235, v43 offset:256
	v_bfe_u32 v43, v42, 16, 1
	v_add3_u32 v42, v42, v43, s22
	ds_write_b16_d16_hi v235, v42 offset:320
	v_fmamk_f32 v42, v48, 0x3c800000, v233
	v_cmp_gt_f32_e32 vcc, s19, v42
	v_mul_f32_e32 v43, 0x4f800000, v42
	s_nop 0
	v_cndmask_b32_e32 v42, v42, v43, vcc
	v_sqrt_f32_e32 v43, v42
	s_nop 0
	v_add_u32_e32 v44, -1, v43
	v_fma_f32 v45, -v44, v43, v42
	v_cmp_ge_f32_e64 s[82:83], 0, v45
	v_add_u32_e32 v45, 1, v43
	s_nop 0
	v_cndmask_b32_e64 v44, v43, v44, s[82:83]
	v_fma_f32 v43, -v45, v43, v42
	v_cmp_lt_f32_e64 s[82:83], 0, v43
	s_nop 1
	v_cndmask_b32_e64 v43, v44, v45, s[82:83]
	v_mul_f32_e32 v44, 0x37800000, v43
	v_cndmask_b32_e32 v43, v43, v44, vcc
	v_cmp_class_f32_e32 vcc, v42, v234
	s_nop 1
	v_cndmask_b32_e32 v42, v43, v42, vcc
	v_div_scale_f32 v43, s[2:3], v42, v42, 1.0
	v_rcp_f32_e32 v44, v43
	s_nop 0
	v_fma_f32 v45, -v43, v44, 1.0
	v_fmac_f32_e32 v44, v45, v44
	v_div_scale_f32 v45, vcc, 1.0, v42, 1.0
	v_mul_f32_e32 v46, v45, v44
	v_fma_f32 v47, -v43, v46, v45
	v_fmac_f32_e32 v46, v47, v44
	v_fma_f32 v43, -v43, v46, v45
	v_div_fmas_f32 v43, v43, v44, v46
	v_div_fixup_f32 v42, v43, v42, 1.0
	v_mul_f32_e32 v41, v41, v42
	v_mul_f32_e32 v41, v41, v15
	v_bfe_u32 v43, v41, 16, 1
	v_mul_f32_e32 v40, v40, v42
	v_add3_u32 v41, v41, v43, s22
	v_mul_f32_e32 v40, v40, v16
	ds_write_b16_d16_hi v235, v41 offset:384
	v_bfe_u32 v41, v40, 16, 1
	v_add3_u32 v40, v40, v41, s22
	ds_write_b16_d16_hi v235, v40 offset:448
	v_cmp_gt_f32_e32 vcc, s19, v33
	v_mul_f32_e32 v40, 0x4f800000, v33
	s_nop 0
	v_cndmask_b32_e32 v33, v33, v40, vcc
	v_sqrt_f32_e32 v40, v33
	s_nop 0
	v_add_u32_e32 v41, -1, v40
	v_fma_f32 v42, -v41, v40, v33
	v_cmp_ge_f32_e64 s[82:83], 0, v42
	v_add_u32_e32 v42, 1, v40
	s_nop 0
	v_cndmask_b32_e64 v41, v40, v41, s[82:83]
	v_fma_f32 v40, -v42, v40, v33
	v_cmp_lt_f32_e64 s[82:83], 0, v40
	s_nop 1
	v_cndmask_b32_e64 v40, v41, v42, s[82:83]
	v_mul_f32_e32 v41, 0x37800000, v40
	v_cndmask_b32_e32 v40, v40, v41, vcc
	v_cmp_class_f32_e32 vcc, v33, v234
	s_nop 1
	v_cndmask_b32_e32 v33, v40, v33, vcc
	v_div_scale_f32 v40, s[2:3], v33, v33, 1.0
	v_rcp_f32_e32 v41, v40
	s_nop 0
	v_fma_f32 v42, -v40, v41, 1.0
	v_fmac_f32_e32 v41, v42, v41
	v_div_scale_f32 v42, vcc, 1.0, v33, 1.0
	v_mul_f32_e32 v43, v42, v41
	v_fma_f32 v44, -v40, v43, v42
	v_fmac_f32_e32 v43, v44, v41
	v_fma_f32 v40, -v40, v43, v42
	v_div_fmas_f32 v40, v40, v41, v43
	v_div_fixup_f32 v33, v40, v33, 1.0
	v_mul_f32_e32 v39, v39, v33
	v_mul_f32_e32 v33, v38, v33
	v_mul_f32_e32 v33, v33, v16
	v_bfe_u32 v38, v33, 16, 1
	v_add3_u32 v33, v33, v38, s22
	ds_write_b16_d16_hi v235, v33 offset:1088
	v_cmp_gt_f32_e32 vcc, s19, v32
	v_mul_f32_e32 v33, 0x4f800000, v32
	v_mul_f32_e32 v39, v39, v15
	v_cndmask_b32_e32 v32, v32, v33, vcc
	v_sqrt_f32_e32 v33, v32
	v_bfe_u32 v40, v39, 16, 1
	v_add3_u32 v39, v39, v40, s22
	ds_write_b16_d16_hi v235, v39 offset:1024
	v_add_u32_e32 v38, -1, v33
	v_fma_f32 v39, -v38, v33, v32
	v_cmp_ge_f32_e64 s[82:83], 0, v39
	v_add_u32_e32 v39, 1, v33
	s_nop 0
	v_cndmask_b32_e64 v38, v33, v38, s[82:83]
	v_fma_f32 v33, -v39, v33, v32
	v_cmp_lt_f32_e64 s[82:83], 0, v33
	s_nop 1
	v_cndmask_b32_e64 v33, v38, v39, s[82:83]
	v_mul_f32_e32 v38, 0x37800000, v33
	v_cndmask_b32_e32 v33, v33, v38, vcc
	v_cmp_class_f32_e32 vcc, v32, v234
	s_nop 1
	v_cndmask_b32_e32 v32, v33, v32, vcc
	v_div_scale_f32 v33, s[2:3], v32, v32, 1.0
	v_rcp_f32_e32 v38, v33
	s_nop 0
	v_fma_f32 v39, -v33, v38, 1.0
	v_fmac_f32_e32 v38, v39, v38
	v_div_scale_f32 v39, vcc, 1.0, v32, 1.0
	v_mul_f32_e32 v40, v39, v38
	v_fma_f32 v41, -v33, v40, v39
	v_fmac_f32_e32 v40, v41, v38
	v_fma_f32 v33, -v33, v40, v39
	v_div_fmas_f32 v33, v33, v38, v40
	v_div_fixup_f32 v32, v33, v32, 1.0
	v_mul_f32_e32 v33, v37, v32
	v_mul_f32_e32 v33, v33, v15
	v_bfe_u32 v37, v33, 16, 1
	v_mul_f32_e32 v32, v36, v32
	v_add3_u32 v33, v33, v37, s22
	v_mul_f32_e32 v32, v32, v16
	ds_write_b16_d16_hi v235, v33 offset:1152
	v_bfe_u32 v33, v32, 16, 1
	v_add3_u32 v32, v32, v33, s22
	ds_write_b16_d16_hi v235, v32 offset:1216
	v_cmp_gt_f32_e32 vcc, s19, v31
	v_mul_f32_e32 v32, 0x4f800000, v31
	s_nop 0
	v_cndmask_b32_e32 v31, v31, v32, vcc
	v_sqrt_f32_e32 v32, v31
	s_nop 0
	v_add_u32_e32 v33, -1, v32
	v_fma_f32 v36, -v33, v32, v31
	v_cmp_ge_f32_e64 s[82:83], 0, v36
	v_add_u32_e32 v36, 1, v32
	s_nop 0
	v_cndmask_b32_e64 v33, v32, v33, s[82:83]
	v_fma_f32 v32, -v36, v32, v31
	v_cmp_lt_f32_e64 s[82:83], 0, v32
	s_nop 1
	v_cndmask_b32_e64 v32, v33, v36, s[82:83]
	v_mul_f32_e32 v33, 0x37800000, v32
	v_cndmask_b32_e32 v32, v32, v33, vcc
	v_cmp_class_f32_e32 vcc, v31, v234
	s_nop 1
	v_cndmask_b32_e32 v31, v32, v31, vcc
	v_div_scale_f32 v32, s[2:3], v31, v31, 1.0
	v_rcp_f32_e32 v33, v32
	s_nop 0
	v_fma_f32 v36, -v32, v33, 1.0
	v_fmac_f32_e32 v33, v36, v33
	v_div_scale_f32 v36, vcc, 1.0, v31, 1.0
	v_mul_f32_e32 v37, v36, v33
	v_fma_f32 v38, -v32, v37, v36
	v_fmac_f32_e32 v37, v38, v33
	v_fma_f32 v32, -v32, v37, v36
	v_div_fmas_f32 v32, v32, v33, v37
	v_div_fixup_f32 v31, v32, v31, 1.0
	v_mul_f32_e32 v32, v35, v31
	v_mul_f32_e32 v32, v32, v15
	v_bfe_u32 v33, v32, 16, 1
	v_mul_f32_e32 v31, v34, v31
	v_add3_u32 v32, v32, v33, s22
	v_mul_f32_e32 v31, v31, v16
	ds_write_b16_d16_hi v235, v32 offset:1280
	v_bfe_u32 v32, v31, 16, 1
	v_add3_u32 v31, v31, v32, s22
	ds_write_b16_d16_hi v235, v31 offset:1344
	v_cmp_gt_f32_e32 vcc, s19, v30
	v_mul_f32_e32 v31, 0x4f800000, v30
	s_nop 0
	v_cndmask_b32_e32 v30, v30, v31, vcc
	v_sqrt_f32_e32 v31, v30
	s_nop 0
	v_add_u32_e32 v32, -1, v31
	v_fma_f32 v33, -v32, v31, v30
	v_cmp_ge_f32_e64 s[82:83], 0, v33
	v_add_u32_e32 v33, 1, v31
	s_nop 0
	v_cndmask_b32_e64 v32, v31, v32, s[82:83]
	v_fma_f32 v31, -v33, v31, v30
	v_cmp_lt_f32_e64 s[82:83], 0, v31
	s_nop 1
	v_cndmask_b32_e64 v31, v32, v33, s[82:83]
	v_mul_f32_e32 v32, 0x37800000, v31
	v_cndmask_b32_e32 v31, v31, v32, vcc
	v_cmp_class_f32_e32 vcc, v30, v234
	s_nop 1
	v_cndmask_b32_e32 v30, v31, v30, vcc
	v_div_scale_f32 v31, s[2:3], v30, v30, 1.0
	v_rcp_f32_e32 v32, v31
	s_nop 0
	v_fma_f32 v33, -v31, v32, 1.0
	v_fmac_f32_e32 v32, v33, v32
	v_div_scale_f32 v33, vcc, 1.0, v30, 1.0
	v_mul_f32_e32 v34, v33, v32
	v_fma_f32 v35, -v31, v34, v33
	v_fmac_f32_e32 v34, v35, v32
	v_fma_f32 v31, -v31, v34, v33
	v_div_fmas_f32 v31, v31, v32, v34
	v_div_fixup_f32 v30, v31, v30, 1.0
	v_mul_f32_e32 v24, v24, v30
	v_mul_f32_e32 v24, v24, v15
	v_bfe_u32 v31, v24, 16, 1
	v_mul_f32_e32 v23, v23, v30
	v_add3_u32 v24, v24, v31, s22
	v_mul_f32_e32 v23, v23, v16
	ds_write_b16_d16_hi v235, v24 offset:1408
	v_bfe_u32 v24, v23, 16, 1
	v_add3_u32 v23, v23, v24, s22
	ds_write_b16_d16_hi v235, v23 offset:1472
	v_fmamk_f32 v23, v29, 0x3c800000, v233
	v_cmp_gt_f32_e32 vcc, s19, v23
	v_mul_f32_e32 v24, 0x4f800000, v23
	s_nop 0
	v_cndmask_b32_e32 v23, v23, v24, vcc
	v_sqrt_f32_e32 v24, v23
	s_nop 0
	v_add_u32_e32 v29, -1, v24
	v_fma_f32 v30, -v29, v24, v23
	v_cmp_ge_f32_e64 s[82:83], 0, v30
	v_add_u32_e32 v30, 1, v24
	s_nop 0
	v_cndmask_b32_e64 v29, v24, v29, s[82:83]
	v_fma_f32 v24, -v30, v24, v23
	v_cmp_lt_f32_e64 s[82:83], 0, v24
	s_nop 1
	v_cndmask_b32_e64 v24, v29, v30, s[82:83]
	v_mul_f32_e32 v29, 0x37800000, v24
	v_cndmask_b32_e32 v24, v24, v29, vcc
	v_cmp_class_f32_e32 vcc, v23, v234
	s_nop 1
	v_cndmask_b32_e32 v23, v24, v23, vcc
	v_div_scale_f32 v24, s[2:3], v23, v23, 1.0
	v_rcp_f32_e32 v29, v24
	s_nop 0
	v_fma_f32 v30, -v24, v29, 1.0
	v_fmac_f32_e32 v29, v30, v29
	v_div_scale_f32 v30, vcc, 1.0, v23, 1.0
	v_mul_f32_e32 v31, v30, v29
	v_fma_f32 v32, -v24, v31, v30
	v_fmac_f32_e32 v31, v32, v29
	v_fma_f32 v24, -v24, v31, v30
	v_div_fmas_f32 v24, v24, v29, v31
	v_div_fixup_f32 v23, v24, v23, 1.0
	v_mul_f32_e32 v22, v22, v23
	v_mul_f32_e32 v22, v22, v15
	v_bfe_u32 v24, v22, 16, 1
	v_mul_f32_e32 v21, v21, v23
	v_add3_u32 v22, v22, v24, s22
	v_mul_f32_e32 v21, v21, v16
	ds_write_b16_d16_hi v235, v22 offset:2048
	v_bfe_u32 v22, v21, 16, 1
	v_add3_u32 v21, v21, v22, s22
	ds_write_b16_d16_hi v235, v21 offset:2112
	v_fmamk_f32 v21, v28, 0x3c800000, v233
	v_cmp_gt_f32_e32 vcc, s19, v21
	v_mul_f32_e32 v22, 0x4f800000, v21
	s_nop 0
	v_cndmask_b32_e32 v21, v21, v22, vcc
	v_sqrt_f32_e32 v22, v21
	s_nop 0
	v_add_u32_e32 v23, -1, v22
	v_fma_f32 v24, -v23, v22, v21
	v_cmp_ge_f32_e64 s[82:83], 0, v24
	v_add_u32_e32 v24, 1, v22
	s_nop 0
	v_cndmask_b32_e64 v23, v22, v23, s[82:83]
	v_fma_f32 v22, -v24, v22, v21
	v_cmp_lt_f32_e64 s[82:83], 0, v22
	s_nop 1
	v_cndmask_b32_e64 v22, v23, v24, s[82:83]
	v_mul_f32_e32 v23, 0x37800000, v22
	v_cndmask_b32_e32 v22, v22, v23, vcc
	v_cmp_class_f32_e32 vcc, v21, v234
	s_nop 1
	v_cndmask_b32_e32 v21, v22, v21, vcc
	v_div_scale_f32 v22, s[2:3], v21, v21, 1.0
	v_rcp_f32_e32 v23, v22
	s_nop 0
	v_fma_f32 v24, -v22, v23, 1.0
	v_fmac_f32_e32 v23, v24, v23
	v_div_scale_f32 v24, vcc, 1.0, v21, 1.0
	v_mul_f32_e32 v28, v24, v23
	v_fma_f32 v29, -v22, v28, v24
	v_fmac_f32_e32 v28, v29, v23
	v_fma_f32 v22, -v22, v28, v24
	v_div_fmas_f32 v22, v22, v23, v28
	v_div_fixup_f32 v21, v22, v21, 1.0
	v_mul_f32_e32 v20, v20, v21
	v_mul_f32_e32 v20, v15, v20
	v_bfe_u32 v22, v20, 16, 1
	v_mul_f32_e32 v19, v19, v21
	v_add3_u32 v20, v20, v22, s22
	v_mul_f32_e32 v19, v19, v16
	ds_write_b16_d16_hi v235, v20 offset:2176
	v_bfe_u32 v20, v19, 16, 1
	v_add3_u32 v19, v19, v20, s22
	ds_write_b16_d16_hi v235, v19 offset:2240
	v_fmamk_f32 v19, v27, 0x3c800000, v233
	v_cmp_gt_f32_e32 vcc, s19, v19
	v_mul_f32_e32 v20, 0x4f800000, v19
	s_nop 0
	v_cndmask_b32_e32 v19, v19, v20, vcc
	v_sqrt_f32_e32 v20, v19
	s_nop 0
	v_add_u32_e32 v21, -1, v20
	v_fma_f32 v22, -v21, v20, v19
	v_cmp_ge_f32_e64 s[82:83], 0, v22
	v_add_u32_e32 v22, 1, v20
	s_nop 0
	v_cndmask_b32_e64 v21, v20, v21, s[82:83]
	v_fma_f32 v20, -v22, v20, v19
	v_cmp_lt_f32_e64 s[82:83], 0, v20
	s_nop 1
	v_cndmask_b32_e64 v20, v21, v22, s[82:83]
	v_mul_f32_e32 v21, 0x37800000, v20
	v_cndmask_b32_e32 v20, v20, v21, vcc
	v_cmp_class_f32_e32 vcc, v19, v234
	s_nop 1
	v_cndmask_b32_e32 v19, v20, v19, vcc
	v_div_scale_f32 v20, s[2:3], v19, v19, 1.0
	v_rcp_f32_e32 v21, v20
	s_nop 0
	v_fma_f32 v22, -v20, v21, 1.0
	v_fmac_f32_e32 v21, v22, v21
	v_div_scale_f32 v22, vcc, 1.0, v19, 1.0
	v_mul_f32_e32 v23, v22, v21
	v_fma_f32 v24, -v20, v23, v22
	v_fmac_f32_e32 v23, v24, v21
	v_fma_f32 v20, -v20, v23, v22
	v_div_fmas_f32 v20, v20, v21, v23
	v_div_fixup_f32 v19, v20, v19, 1.0
	v_mul_f32_e32 v18, v18, v19
	v_mul_f32_e32 v18, v15, v18
	v_bfe_u32 v20, v18, 16, 1
	v_mul_f32_e32 v11, v11, v19
	v_add3_u32 v18, v18, v20, s22
	v_mul_f32_e32 v11, v16, v11
	ds_write_b16_d16_hi v235, v18 offset:2304
	v_bfe_u32 v18, v11, 16, 1
	v_add3_u32 v11, v11, v18, s22
	ds_write_b16_d16_hi v235, v11 offset:2368
	v_fmamk_f32 v11, v26, 0x3c800000, v233
	v_cmp_gt_f32_e32 vcc, s19, v11
	v_mul_f32_e32 v18, 0x4f800000, v11
	s_nop 0
	v_cndmask_b32_e32 v11, v11, v18, vcc
	v_sqrt_f32_e32 v18, v11
	s_nop 0
	v_add_u32_e32 v19, -1, v18
	v_fma_f32 v20, -v19, v18, v11
	v_cmp_ge_f32_e64 s[82:83], 0, v20
	v_add_u32_e32 v20, 1, v18
	s_nop 0
	v_cndmask_b32_e64 v19, v18, v19, s[82:83]
	v_fma_f32 v18, -v20, v18, v11
	v_cmp_lt_f32_e64 s[82:83], 0, v18
	s_nop 1
	v_cndmask_b32_e64 v18, v19, v20, s[82:83]
	v_mul_f32_e32 v19, 0x37800000, v18
	v_cndmask_b32_e32 v18, v18, v19, vcc
	v_cmp_class_f32_e32 vcc, v11, v234
	s_nop 1
	v_cndmask_b32_e32 v11, v18, v11, vcc
	v_div_scale_f32 v18, s[2:3], v11, v11, 1.0
	v_rcp_f32_e32 v19, v18
	s_nop 0
	v_fma_f32 v20, -v18, v19, 1.0
	v_fmac_f32_e32 v19, v20, v19
	v_div_scale_f32 v20, vcc, 1.0, v11, 1.0
	v_mul_f32_e32 v21, v20, v19
	v_fma_f32 v22, -v18, v21, v20
	v_fmac_f32_e32 v21, v22, v19
	v_fma_f32 v18, -v18, v21, v20
	v_div_fmas_f32 v18, v18, v19, v21
	v_div_fixup_f32 v11, v18, v11, 1.0
	v_mul_f32_e32 v7, v7, v11
	v_mul_f32_e32 v7, v15, v7
	v_bfe_u32 v18, v7, 16, 1
	v_mul_f32_e32 v6, v6, v11
	v_add3_u32 v7, v7, v18, s22
	v_mul_f32_e32 v6, v16, v6
	ds_write_b16_d16_hi v235, v7 offset:2432
	v_bfe_u32 v7, v6, 16, 1
	v_add3_u32 v6, v6, v7, s22
	ds_write_b16_d16_hi v235, v6 offset:2496
	v_fmamk_f32 v6, v25, 0x3c800000, v233
	v_cmp_gt_f32_e32 vcc, s19, v6
	v_mul_f32_e32 v7, 0x4f800000, v6
	s_nop 0
	v_cndmask_b32_e32 v6, v6, v7, vcc
	v_sqrt_f32_e32 v7, v6
	s_nop 0
	v_add_u32_e32 v11, -1, v7
	v_fma_f32 v18, -v11, v7, v6
	v_cmp_ge_f32_e64 s[82:83], 0, v18
	v_add_u32_e32 v18, 1, v7
	s_nop 0
	v_cndmask_b32_e64 v11, v7, v11, s[82:83]
	v_fma_f32 v7, -v18, v7, v6
	v_cmp_lt_f32_e64 s[82:83], 0, v7
	s_nop 1
	v_cndmask_b32_e64 v7, v11, v18, s[82:83]
	v_mul_f32_e32 v11, 0x37800000, v7
	v_cndmask_b32_e32 v7, v7, v11, vcc
	v_cmp_class_f32_e32 vcc, v6, v234
	s_nop 1
	v_cndmask_b32_e32 v6, v7, v6, vcc
	v_div_scale_f32 v7, s[2:3], v6, v6, 1.0
	v_rcp_f32_e32 v11, v7
	s_nop 0
	v_fma_f32 v18, -v7, v11, 1.0
	v_fmac_f32_e32 v11, v18, v11
	v_div_scale_f32 v18, vcc, 1.0, v6, 1.0
	v_mul_f32_e32 v19, v18, v11
	v_fma_f32 v20, -v7, v19, v18
	v_fmac_f32_e32 v19, v20, v11
	v_fma_f32 v7, -v7, v19, v18
	v_div_fmas_f32 v7, v7, v11, v19
	v_div_fixup_f32 v6, v7, v6, 1.0
	v_mul_f32_e32 v7, v12, v6
	v_mul_f32_e32 v7, v15, v7
	v_bfe_u32 v11, v7, 16, 1
	v_mul_f32_e32 v6, v10, v6
	v_add3_u32 v7, v7, v11, s22
	v_mul_f32_e32 v6, v16, v6
	ds_write_b16_d16_hi v235, v7 offset:3072
	v_bfe_u32 v7, v6, 16, 1
	v_add3_u32 v6, v6, v7, s22
	ds_write_b16_d16_hi v235, v6 offset:3136
	v_fmamk_f32 v6, v17, 0x3c800000, v233
	v_cmp_gt_f32_e32 vcc, s19, v6
	v_mul_f32_e32 v7, 0x4f800000, v6
	s_nop 0
	v_cndmask_b32_e32 v6, v6, v7, vcc
	v_sqrt_f32_e32 v7, v6
	s_nop 0
	v_add_u32_e32 v10, -1, v7
	v_fma_f32 v11, -v10, v7, v6
	v_cmp_ge_f32_e64 s[82:83], 0, v11
	v_add_u32_e32 v11, 1, v7
	s_nop 0
	v_cndmask_b32_e64 v10, v7, v10, s[82:83]
	v_fma_f32 v7, -v11, v7, v6
	v_cmp_lt_f32_e64 s[82:83], 0, v7
	s_nop 1
	v_cndmask_b32_e64 v7, v10, v11, s[82:83]
	v_mul_f32_e32 v10, 0x37800000, v7
	v_cndmask_b32_e32 v7, v7, v10, vcc
	v_cmp_class_f32_e32 vcc, v6, v234
	s_nop 1
	v_cndmask_b32_e32 v6, v7, v6, vcc
	v_div_scale_f32 v7, s[2:3], v6, v6, 1.0
	v_rcp_f32_e32 v10, v7
	s_nop 0
	v_fma_f32 v11, -v7, v10, 1.0
	v_fmac_f32_e32 v10, v11, v10
	v_div_scale_f32 v11, vcc, 1.0, v6, 1.0
	v_mul_f32_e32 v12, v11, v10
	v_fma_f32 v17, -v7, v12, v11
	v_fmac_f32_e32 v12, v17, v10
	v_fma_f32 v7, -v7, v12, v11
	v_div_fmas_f32 v7, v7, v10, v12
	v_div_fixup_f32 v6, v7, v6, 1.0
	v_mul_f32_e32 v7, v9, v6
	v_mul_f32_e32 v7, v15, v7
	v_bfe_u32 v9, v7, 16, 1
	v_mul_f32_e32 v6, v8, v6
	v_add3_u32 v7, v7, v9, s22
	v_mul_f32_e32 v6, v16, v6
	ds_write_b16_d16_hi v235, v7 offset:3200
	v_bfe_u32 v7, v6, 16, 1
	v_add3_u32 v6, v6, v7, s22
	ds_write_b16_d16_hi v235, v6 offset:3264
	v_fmamk_f32 v6, v14, 0x3c800000, v233
	v_cmp_gt_f32_e32 vcc, s19, v6
	v_mul_f32_e32 v7, 0x4f800000, v6
	s_nop 0
	v_cndmask_b32_e32 v6, v6, v7, vcc
	v_sqrt_f32_e32 v7, v6
	s_nop 0
	v_add_u32_e32 v8, -1, v7
	v_fma_f32 v9, -v8, v7, v6
	v_cmp_ge_f32_e64 s[82:83], 0, v9
	v_add_u32_e32 v9, 1, v7
	s_nop 0
	v_cndmask_b32_e64 v8, v7, v8, s[82:83]
	v_fma_f32 v7, -v9, v7, v6
	v_cmp_lt_f32_e64 s[82:83], 0, v7
	s_nop 1
	v_cndmask_b32_e64 v7, v8, v9, s[82:83]
	v_mul_f32_e32 v8, 0x37800000, v7
	v_cndmask_b32_e32 v7, v7, v8, vcc
	v_cmp_class_f32_e32 vcc, v6, v234
	s_nop 1
	v_cndmask_b32_e32 v6, v7, v6, vcc
	v_div_scale_f32 v7, s[2:3], v6, v6, 1.0
	v_rcp_f32_e32 v8, v7
	s_nop 0
	v_fma_f32 v9, -v7, v8, 1.0
	v_fmac_f32_e32 v8, v9, v8
	v_div_scale_f32 v9, vcc, 1.0, v6, 1.0
	v_mul_f32_e32 v10, v9, v8
	v_fma_f32 v11, -v7, v10, v9
	v_fmac_f32_e32 v10, v11, v8
	v_fma_f32 v7, -v7, v10, v9
	v_div_fmas_f32 v7, v7, v8, v10
	v_div_fixup_f32 v6, v7, v6, 1.0
	v_mul_f32_e32 v5, v5, v6
	v_mul_f32_e32 v5, v15, v5
	v_bfe_u32 v7, v5, 16, 1
	v_mul_f32_e32 v4, v4, v6
	v_add3_u32 v5, v5, v7, s22
	v_mul_f32_e32 v4, v16, v4
	ds_write_b16_d16_hi v235, v5 offset:3328
	v_bfe_u32 v5, v4, 16, 1
	v_add3_u32 v4, v4, v5, s22
	ds_write_b16_d16_hi v235, v4 offset:3392
	v_fmamk_f32 v4, v13, 0x3c800000, v233
	v_cmp_gt_f32_e32 vcc, s19, v4
	v_mul_f32_e32 v5, 0x4f800000, v4
	s_nop 0
	v_cndmask_b32_e32 v4, v4, v5, vcc
	v_sqrt_f32_e32 v5, v4
	s_nop 0
	v_add_u32_e32 v6, -1, v5
	v_fma_f32 v7, -v6, v5, v4
	v_cmp_ge_f32_e64 s[82:83], 0, v7
	v_add_u32_e32 v7, 1, v5
	s_nop 0
	v_cndmask_b32_e64 v6, v5, v6, s[82:83]
	v_fma_f32 v5, -v7, v5, v4
	v_cmp_lt_f32_e64 s[82:83], 0, v5
	s_nop 1
	v_cndmask_b32_e64 v5, v6, v7, s[82:83]
	v_mul_f32_e32 v6, 0x37800000, v5
	v_cndmask_b32_e32 v5, v5, v6, vcc
	v_cmp_class_f32_e32 vcc, v4, v234
	s_nop 1
	v_cndmask_b32_e32 v4, v5, v4, vcc
	v_div_scale_f32 v5, s[2:3], v4, v4, 1.0
	v_rcp_f32_e32 v6, v5
	s_add_u32 s2, s16, s23
	s_addc_u32 s3, s17, 0
	v_fma_f32 v7, -v5, v6, 1.0
	v_fmac_f32_e32 v6, v7, v6
	v_div_scale_f32 v7, vcc, 1.0, v4, 1.0
	v_mul_f32_e32 v8, v7, v6
	v_fma_f32 v9, -v5, v8, v7
	v_fmac_f32_e32 v8, v9, v6
	v_fma_f32 v5, -v5, v8, v7
	v_div_fmas_f32 v5, v5, v6, v8
	v_div_fixup_f32 v4, v5, v4, 1.0
	v_mul_f32_e32 v3, v3, v4
	v_mul_f32_e32 v3, v15, v3
	v_bfe_u32 v5, v3, 16, 1
	v_mul_f32_e32 v2, v2, v4
	v_add3_u32 v3, v3, v5, s22
	v_mul_f32_e32 v2, v16, v2
	ds_write_b16_d16_hi v235, v3 offset:3456
	v_bfe_u32 v3, v2, 16, 1
	v_add3_u32 v2, v2, v3, s22
	ds_write_b16_d16_hi v235, v2 offset:3520
	s_waitcnt lgkmcnt(0)
	ds_read_b128 v[2:5], v236
	v_mov_b32_e32 v9, s3
	v_or_b32_e32 v8, s2, v176
	v_lshl_add_u64 v[6:7], v[178:179], 0, s[14:15]
	v_lshlrev_b64 v[8:9], 11, v[8:9]
	v_lshl_add_u64 v[8:9], v[6:7], 0, v[8:9]
	s_waitcnt lgkmcnt(0)
	global_store_dwordx4 v[8:9], v[2:5], off
	ds_read_b128 v[2:5], v237
	v_mov_b32_e32 v9, s3
	v_or_b32_e32 v8, s2, v180
	v_lshlrev_b64 v[8:9], 11, v[8:9]
	v_lshl_add_u64 v[8:9], v[6:7], 0, v[8:9]
	s_waitcnt lgkmcnt(0)
	global_store_dwordx4 v[8:9], v[2:5], off
	ds_read_b128 v[2:5], v238
	v_mov_b32_e32 v9, s3
	v_or_b32_e32 v8, s2, v182
	v_lshlrev_b64 v[8:9], 11, v[8:9]
	v_lshl_add_u64 v[8:9], v[6:7], 0, v[8:9]
	s_waitcnt lgkmcnt(0)
	global_store_dwordx4 v[8:9], v[2:5], off
	ds_read_b128 v[2:5], v239
	v_mov_b32_e32 v9, s3
	v_or_b32_e32 v8, s2, v184
	v_lshlrev_b64 v[8:9], 11, v[8:9]
	v_lshl_add_u64 v[6:7], v[6:7], 0, v[8:9]
	s_waitcnt lgkmcnt(0)
	global_store_dwordx4 v[6:7], v[2:5], off
	s_waitcnt vmcnt(0) lgkmcnt(0)
	s_barrier
	s_mov_b64 s[2:3], 0

.LBB0_716:
	s_setprio 0
	v_readlane_b32 s88, v253, 5
	v_readlane_b32 s76, v253, 59
	v_readlane_b32 s90, v252, 14
	v_readlane_b32 s75, v252, 1
	v_readlane_b32 s69, v253, 56
	v_readlane_b32 s66, v252, 4
	v_readlane_b32 s89, v253, 6
	v_readlane_b32 s68, v253, 57
	v_readlane_b32 s77, v253, 60
	v_readlane_b32 s78, v253, 61
	v_readlane_b32 s79, v253, 62
	v_readlane_b32 s96, v252, 6
	v_readlane_b32 s86, v252, 54
	v_readlane_b32 s91, v252, 15
	v_readlane_b32 s67, v252, 5
	v_readlane_b32 s87, v252, 55
